# scanner: operand reads of a step issued one slot earlier (two steps at the chunk start, none in the last slot) so the chunk-end LDS drain is covered
# speedup vs baseline: 1.0079x; 1.0079x over previous
.LBB0_787:
	s_and_saveexec_b64 s[0:1], s[8:9]
	s_xor_b64 s[36:37], exec, s[0:1]
	s_cbranch_execz .LBB0_791
	s_and_saveexec_b64 s[44:45], s[26:27]
	s_cbranch_execz .LBB0_790
	s_and_b32 s0, s54, 1
	s_mul_i32 s1, s0, 0xc000
	s_lshl_b32 s4, s30, 2
	v_add_u32_e32 v10, s1, v97
	s_add_i32 s1, s1, s4
	v_lshl_add_u32 v11, v95, 2, s1
	v_lshl_add_u32 v12, s0, 14, v102
	v_pk_fma_f32 v[4:5], v[60:61], v[64:65], v[56:57] op_sel_hi:[0,1,1]
	v_pk_fma_f32 v[6:7], v[60:61], v[66:67], v[58:59] op_sel_hi:[0,1,1]
	v_pk_mul_f32 v[80:81], v[4:5], v[80:81]
	v_pk_fma_f32 v[80:81], v[6:7], v[82:83], v[80:81]
	v_add_f32_e32 v80, v80, v81
	v_pk_mul_f32 v[76:77], v[76:77], v[2:3] op_sel_hi:[1,0]
	v_pk_mul_f32 v[78:79], v[78:79], v[2:3] op_sel_hi:[1,0]
	v_add_f32_dpp v80, v80, v80 quad_perm:[1,0,3,2] row_mask:0xf bank_mask:0xf bound_ctrl:1
	v_pk_fma_f32 v[76:77], v[4:5], v[68:69], v[76:77]
	v_pk_fma_f32 v[78:79], v[6:7], v[70:71], v[78:79]
	v_add_f32_dpp v80, v80, v80 quad_perm:[2,3,0,1] row_mask:0xf bank_mask:0xf bound_ctrl:1
	v_pk_mul_f32 v[52:53], v[52:53], v[4:5]
	v_pk_fma_f32 v[52:53], v[6:7], v[54:55], v[52:53]
	v_add_f32_dpp v80, v80, v80 row_half_mirror row_mask:0xf bank_mask:0xf bound_ctrl:1
	v_add_f32_e32 v9, v52, v53
	ds_read_b128 v[36:39], v10 offset:512
	ds_read2st64_b32 v[0:1], v11 offset0:5 offset1:11
	ds_read_b128 v[40:43], v10 offset:768
	ds_read_b128 v[28:31], v10 offset:0
	ds_read_b128 v[44:47], v10 offset:1024
	ds_read_b128 v[32:35], v10 offset:256
	ds_read_b128 v[56:59], v10 offset:2048
	ds_read_b128 v[60:63], v10 offset:2304
	ds_read_b128 v[48:51], v10 offset:1536
	ds_read_b128 v[64:67], v10 offset:2560
	ds_read_b128 v[52:55], v10 offset:1792
	v_add_f32_dpp v80, v80, v80 row_mirror row_mask:0xf bank_mask:0xf bound_ctrl:1
	v_pk_fma_f32 v[4:5], v[80:81], v[84:85], v[76:77] op_sel_hi:[0,1,1]
	v_pk_fma_f32 v[6:7], v[80:81], v[86:87], v[78:79] op_sel_hi:[0,1,1]
	v_pk_mul_f32 v[116:117], v[4:5], v[116:117]
	v_pk_fma_f32 v[116:117], v[6:7], v[118:119], v[116:117]
	v_add_f32_e32 v116, v116, v117
	v_pk_mul_f32 v[112:113], v[112:113], v[2:3] op_sel:[0,1] op_sel_hi:[1,1]
	v_pk_mul_f32 v[114:115], v[114:115], v[2:3] op_sel:[0,1] op_sel_hi:[1,1]
	v_add_f32_dpp v116, v116, v116 quad_perm:[1,0,3,2] row_mask:0xf bank_mask:0xf bound_ctrl:1
	v_pk_fma_f32 v[112:113], v[4:5], v[104:105], v[112:113]
	v_pk_fma_f32 v[114:115], v[6:7], v[106:107], v[114:115]
	v_add_f32_dpp v116, v116, v116 quad_perm:[2,3,0,1] row_mask:0xf bank_mask:0xf bound_ctrl:1
	v_pk_mul_f32 v[72:73], v[72:73], v[4:5]
	v_pk_fma_f32 v[72:73], v[6:7], v[74:75], v[72:73]
	v_add_f32_dpp v116, v116, v116 row_half_mirror row_mask:0xf bank_mask:0xf bound_ctrl:1
	v_add_f32_e32 v8, v72, v73
	ds_read_b128 v[76:79], v10 offset:3584
	ds_read2st64_b32 v[2:3], v11 offset0:17 offset1:23
	ds_read_b128 v[80:83], v10 offset:3840
	ds_read_b128 v[68:71], v10 offset:3072
	ds_read_b128 v[84:87], v10 offset:4096
	ds_read_b128 v[72:75], v10 offset:3328
	ds_write2st64_b32 v12, v9, v8 offset0:0 offset1:2
	v_add_f32_dpp v116, v116, v116 row_mirror row_mask:0xf bank_mask:0xf bound_ctrl:1
	v_pk_fma_f32 v[4:5], v[116:117], v[120:121], v[112:113] op_sel_hi:[0,1,1]
	v_pk_fma_f32 v[6:7], v[116:117], v[122:123], v[114:115] op_sel_hi:[0,1,1]
	s_waitcnt lgkmcnt(12)
	v_pk_mul_f32 v[40:41], v[4:5], v[40:41]
	v_pk_fma_f32 v[40:41], v[6:7], v[42:43], v[40:41]
	v_add_f32_e32 v40, v40, v41
	v_pk_mul_f32 v[36:37], v[36:37], v[0:1] op_sel_hi:[1,0]
	v_pk_mul_f32 v[38:39], v[38:39], v[0:1] op_sel_hi:[1,0]
	v_add_f32_dpp v40, v40, v40 quad_perm:[1,0,3,2] row_mask:0xf bank_mask:0xf bound_ctrl:1
	v_pk_fma_f32 v[36:37], v[4:5], v[28:29], v[36:37]
	v_pk_fma_f32 v[38:39], v[6:7], v[30:31], v[38:39]
	v_add_f32_dpp v40, v40, v40 quad_perm:[2,3,0,1] row_mask:0xf bank_mask:0xf bound_ctrl:1
	v_pk_mul_f32 v[108:109], v[108:109], v[4:5]
	v_pk_fma_f32 v[108:109], v[6:7], v[110:111], v[108:109]
	v_add_f32_dpp v40, v40, v40 row_half_mirror row_mask:0xf bank_mask:0xf bound_ctrl:1
	v_add_f32_e32 v9, v108, v109
	ds_read_b128 v[112:115], v10 offset:5120
	ds_read_b128 v[116:119], v10 offset:5376
	ds_read_b128 v[104:107], v10 offset:4608
	ds_read_b128 v[120:123], v10 offset:5632
	ds_read_b128 v[108:111], v10 offset:4864
	v_add_f32_dpp v40, v40, v40 row_mirror row_mask:0xf bank_mask:0xf bound_ctrl:1
	v_pk_fma_f32 v[4:5], v[40:41], v[44:45], v[36:37] op_sel_hi:[0,1,1]
	v_pk_fma_f32 v[6:7], v[40:41], v[46:47], v[38:39] op_sel_hi:[0,1,1]
	s_waitcnt lgkmcnt(12)
	v_pk_mul_f32 v[60:61], v[4:5], v[60:61]
	v_pk_fma_f32 v[60:61], v[6:7], v[62:63], v[60:61]
	v_add_f32_e32 v60, v60, v61
	v_pk_mul_f32 v[56:57], v[56:57], v[0:1] op_sel:[0,1] op_sel_hi:[1,1]
	v_pk_mul_f32 v[58:59], v[58:59], v[0:1] op_sel:[0,1] op_sel_hi:[1,1]
	v_add_f32_dpp v60, v60, v60 quad_perm:[1,0,3,2] row_mask:0xf bank_mask:0xf bound_ctrl:1
	v_pk_fma_f32 v[56:57], v[4:5], v[48:49], v[56:57]
	v_pk_fma_f32 v[58:59], v[6:7], v[50:51], v[58:59]
	v_add_f32_dpp v60, v60, v60 quad_perm:[2,3,0,1] row_mask:0xf bank_mask:0xf bound_ctrl:1
	v_pk_mul_f32 v[32:33], v[32:33], v[4:5]
	v_pk_fma_f32 v[32:33], v[6:7], v[34:35], v[32:33]
	v_add_f32_dpp v60, v60, v60 row_half_mirror row_mask:0xf bank_mask:0xf bound_ctrl:1
	v_add_f32_e32 v8, v32, v33
	ds_read_b128 v[36:39], v10 offset:6656
	ds_read2st64_b32 v[0:1], v11 offset0:29 offset1:35
	ds_read_b128 v[40:43], v10 offset:6912
	ds_read_b128 v[28:31], v10 offset:6144
	ds_read_b128 v[44:47], v10 offset:7168
	ds_read_b128 v[32:35], v10 offset:6400
	ds_write2st64_b32 v12, v9, v8 offset0:4 offset1:6
	v_add_f32_dpp v60, v60, v60 row_mirror row_mask:0xf bank_mask:0xf bound_ctrl:1
	v_pk_fma_f32 v[4:5], v[60:61], v[64:65], v[56:57] op_sel_hi:[0,1,1]
	v_pk_fma_f32 v[6:7], v[60:61], v[66:67], v[58:59] op_sel_hi:[0,1,1]
	s_waitcnt lgkmcnt(13)
	v_pk_mul_f32 v[80:81], v[4:5], v[80:81]
	v_pk_fma_f32 v[80:81], v[6:7], v[82:83], v[80:81]
	v_add_f32_e32 v80, v80, v81
	v_pk_mul_f32 v[76:77], v[76:77], v[2:3] op_sel_hi:[1,0]
	v_pk_mul_f32 v[78:79], v[78:79], v[2:3] op_sel_hi:[1,0]
	v_add_f32_dpp v80, v80, v80 quad_perm:[1,0,3,2] row_mask:0xf bank_mask:0xf bound_ctrl:1
	v_pk_fma_f32 v[76:77], v[4:5], v[68:69], v[76:77]
	v_pk_fma_f32 v[78:79], v[6:7], v[70:71], v[78:79]
	v_add_f32_dpp v80, v80, v80 quad_perm:[2,3,0,1] row_mask:0xf bank_mask:0xf bound_ctrl:1
	v_pk_mul_f32 v[52:53], v[52:53], v[4:5]
	v_pk_fma_f32 v[52:53], v[6:7], v[54:55], v[52:53]
	v_add_f32_dpp v80, v80, v80 row_half_mirror row_mask:0xf bank_mask:0xf bound_ctrl:1
	v_add_f32_e32 v9, v52, v53
	ds_read_b128 v[56:59], v10 offset:8192
	ds_read_b128 v[60:63], v10 offset:8448
	ds_read_b128 v[48:51], v10 offset:7680
	ds_read_b128 v[64:67], v10 offset:8704
	ds_read_b128 v[52:55], v10 offset:7936
	v_add_f32_dpp v80, v80, v80 row_mirror row_mask:0xf bank_mask:0xf bound_ctrl:1
	v_pk_fma_f32 v[4:5], v[80:81], v[84:85], v[76:77] op_sel_hi:[0,1,1]
	v_pk_fma_f32 v[6:7], v[80:81], v[86:87], v[78:79] op_sel_hi:[0,1,1]
	s_waitcnt lgkmcnt(12)
	v_pk_mul_f32 v[116:117], v[4:5], v[116:117]
	v_pk_fma_f32 v[116:117], v[6:7], v[118:119], v[116:117]
	v_add_f32_e32 v116, v116, v117
	v_pk_mul_f32 v[112:113], v[112:113], v[2:3] op_sel:[0,1] op_sel_hi:[1,1]
	v_pk_mul_f32 v[114:115], v[114:115], v[2:3] op_sel:[0,1] op_sel_hi:[1,1]
	v_add_f32_dpp v116, v116, v116 quad_perm:[1,0,3,2] row_mask:0xf bank_mask:0xf bound_ctrl:1
	v_pk_fma_f32 v[112:113], v[4:5], v[104:105], v[112:113]
	v_pk_fma_f32 v[114:115], v[6:7], v[106:107], v[114:115]
	v_add_f32_dpp v116, v116, v116 quad_perm:[2,3,0,1] row_mask:0xf bank_mask:0xf bound_ctrl:1
	v_pk_mul_f32 v[72:73], v[72:73], v[4:5]
	v_pk_fma_f32 v[72:73], v[6:7], v[74:75], v[72:73]
	v_add_f32_dpp v116, v116, v116 row_half_mirror row_mask:0xf bank_mask:0xf bound_ctrl:1
	v_add_f32_e32 v8, v72, v73
	ds_read_b128 v[76:79], v10 offset:9728
	ds_read2st64_b32 v[2:3], v11 offset0:41 offset1:47
	ds_read_b128 v[80:83], v10 offset:9984
	ds_read_b128 v[68:71], v10 offset:9216
	ds_read_b128 v[84:87], v10 offset:10240
	ds_read_b128 v[72:75], v10 offset:9472
	ds_write2st64_b32 v12, v9, v8 offset0:8 offset1:10
	v_add_f32_dpp v116, v116, v116 row_mirror row_mask:0xf bank_mask:0xf bound_ctrl:1
	v_pk_fma_f32 v[4:5], v[116:117], v[120:121], v[112:113] op_sel_hi:[0,1,1]
	v_pk_fma_f32 v[6:7], v[116:117], v[122:123], v[114:115] op_sel_hi:[0,1,1]
	s_waitcnt lgkmcnt(13)
	v_pk_mul_f32 v[40:41], v[4:5], v[40:41]
	v_pk_fma_f32 v[40:41], v[6:7], v[42:43], v[40:41]
	v_add_f32_e32 v40, v40, v41
	v_pk_mul_f32 v[36:37], v[36:37], v[0:1] op_sel_hi:[1,0]
	v_pk_mul_f32 v[38:39], v[38:39], v[0:1] op_sel_hi:[1,0]
	v_add_f32_dpp v40, v40, v40 quad_perm:[1,0,3,2] row_mask:0xf bank_mask:0xf bound_ctrl:1
	v_pk_fma_f32 v[36:37], v[4:5], v[28:29], v[36:37]
	v_pk_fma_f32 v[38:39], v[6:7], v[30:31], v[38:39]
	v_add_f32_dpp v40, v40, v40 quad_perm:[2,3,0,1] row_mask:0xf bank_mask:0xf bound_ctrl:1
	v_pk_mul_f32 v[108:109], v[108:109], v[4:5]
	v_pk_fma_f32 v[108:109], v[6:7], v[110:111], v[108:109]
	v_add_f32_dpp v40, v40, v40 row_half_mirror row_mask:0xf bank_mask:0xf bound_ctrl:1
	v_add_f32_e32 v9, v108, v109
	ds_read_b128 v[112:115], v10 offset:11264
	ds_read_b128 v[116:119], v10 offset:11520
	ds_read_b128 v[104:107], v10 offset:10752
	ds_read_b128 v[120:123], v10 offset:11776
	ds_read_b128 v[108:111], v10 offset:11008
	v_add_f32_dpp v40, v40, v40 row_mirror row_mask:0xf bank_mask:0xf bound_ctrl:1
	v_pk_fma_f32 v[4:5], v[40:41], v[44:45], v[36:37] op_sel_hi:[0,1,1]
	v_pk_fma_f32 v[6:7], v[40:41], v[46:47], v[38:39] op_sel_hi:[0,1,1]
	s_waitcnt lgkmcnt(12)
	v_pk_mul_f32 v[60:61], v[4:5], v[60:61]
	v_pk_fma_f32 v[60:61], v[6:7], v[62:63], v[60:61]
	v_add_f32_e32 v60, v60, v61
	v_pk_mul_f32 v[56:57], v[56:57], v[0:1] op_sel:[0,1] op_sel_hi:[1,1]
	v_pk_mul_f32 v[58:59], v[58:59], v[0:1] op_sel:[0,1] op_sel_hi:[1,1]
	v_add_f32_dpp v60, v60, v60 quad_perm:[1,0,3,2] row_mask:0xf bank_mask:0xf bound_ctrl:1
	v_pk_fma_f32 v[56:57], v[4:5], v[48:49], v[56:57]
	v_pk_fma_f32 v[58:59], v[6:7], v[50:51], v[58:59]
	v_add_f32_dpp v60, v60, v60 quad_perm:[2,3,0,1] row_mask:0xf bank_mask:0xf bound_ctrl:1
	v_pk_mul_f32 v[32:33], v[32:33], v[4:5]
	v_pk_fma_f32 v[32:33], v[6:7], v[34:35], v[32:33]
	v_add_f32_dpp v60, v60, v60 row_half_mirror row_mask:0xf bank_mask:0xf bound_ctrl:1
	v_add_f32_e32 v8, v32, v33
	ds_read_b128 v[36:39], v10 offset:12800
	ds_read2st64_b32 v[0:1], v11 offset0:53 offset1:59
	ds_read_b128 v[40:43], v10 offset:13056
	ds_read_b128 v[28:31], v10 offset:12288
	ds_read_b128 v[44:47], v10 offset:13312
	ds_read_b128 v[32:35], v10 offset:12544
	ds_write2st64_b32 v12, v9, v8 offset0:12 offset1:14
	v_add_f32_dpp v60, v60, v60 row_mirror row_mask:0xf bank_mask:0xf bound_ctrl:1
	v_pk_fma_f32 v[4:5], v[60:61], v[64:65], v[56:57] op_sel_hi:[0,1,1]
	v_pk_fma_f32 v[6:7], v[60:61], v[66:67], v[58:59] op_sel_hi:[0,1,1]
	s_waitcnt lgkmcnt(13)
	v_pk_mul_f32 v[80:81], v[4:5], v[80:81]
	v_pk_fma_f32 v[80:81], v[6:7], v[82:83], v[80:81]
	v_add_f32_e32 v80, v80, v81
	v_pk_mul_f32 v[76:77], v[76:77], v[2:3] op_sel_hi:[1,0]
	v_pk_mul_f32 v[78:79], v[78:79], v[2:3] op_sel_hi:[1,0]
	v_add_f32_dpp v80, v80, v80 quad_perm:[1,0,3,2] row_mask:0xf bank_mask:0xf bound_ctrl:1
	v_pk_fma_f32 v[76:77], v[4:5], v[68:69], v[76:77]
	v_pk_fma_f32 v[78:79], v[6:7], v[70:71], v[78:79]
	v_add_f32_dpp v80, v80, v80 quad_perm:[2,3,0,1] row_mask:0xf bank_mask:0xf bound_ctrl:1
	v_pk_mul_f32 v[52:53], v[52:53], v[4:5]
	v_pk_fma_f32 v[52:53], v[6:7], v[54:55], v[52:53]
	v_add_f32_dpp v80, v80, v80 row_half_mirror row_mask:0xf bank_mask:0xf bound_ctrl:1
	v_add_f32_e32 v9, v52, v53
	ds_read_b128 v[56:59], v10 offset:14336
	ds_read_b128 v[60:63], v10 offset:14592
	ds_read_b128 v[48:51], v10 offset:13824
	ds_read_b128 v[64:67], v10 offset:14848
	ds_read_b128 v[52:55], v10 offset:14080
	v_add_f32_dpp v80, v80, v80 row_mirror row_mask:0xf bank_mask:0xf bound_ctrl:1
	v_pk_fma_f32 v[4:5], v[80:81], v[84:85], v[76:77] op_sel_hi:[0,1,1]
	v_pk_fma_f32 v[6:7], v[80:81], v[86:87], v[78:79] op_sel_hi:[0,1,1]
	s_waitcnt lgkmcnt(12)
	v_pk_mul_f32 v[116:117], v[4:5], v[116:117]
	v_pk_fma_f32 v[116:117], v[6:7], v[118:119], v[116:117]
	v_add_f32_e32 v116, v116, v117
	v_pk_mul_f32 v[112:113], v[112:113], v[2:3] op_sel:[0,1] op_sel_hi:[1,1]
	v_pk_mul_f32 v[114:115], v[114:115], v[2:3] op_sel:[0,1] op_sel_hi:[1,1]
	v_add_f32_dpp v116, v116, v116 quad_perm:[1,0,3,2] row_mask:0xf bank_mask:0xf bound_ctrl:1
	v_pk_fma_f32 v[112:113], v[4:5], v[104:105], v[112:113]
	v_pk_fma_f32 v[114:115], v[6:7], v[106:107], v[114:115]
	v_add_f32_dpp v116, v116, v116 quad_perm:[2,3,0,1] row_mask:0xf bank_mask:0xf bound_ctrl:1
	v_pk_mul_f32 v[72:73], v[72:73], v[4:5]
	v_pk_fma_f32 v[72:73], v[6:7], v[74:75], v[72:73]
	v_add_f32_dpp v116, v116, v116 row_half_mirror row_mask:0xf bank_mask:0xf bound_ctrl:1
	v_add_f32_e32 v8, v72, v73
	ds_read_b128 v[76:79], v10 offset:15872
	ds_read2st64_b32 v[2:3], v11 offset0:65 offset1:71
	ds_read_b128 v[80:83], v10 offset:16128
	ds_read_b128 v[68:71], v10 offset:15360
	ds_read_b128 v[84:87], v10 offset:16384
	ds_read_b128 v[72:75], v10 offset:15616
	ds_write2st64_b32 v12, v9, v8 offset0:16 offset1:18
	v_add_f32_dpp v116, v116, v116 row_mirror row_mask:0xf bank_mask:0xf bound_ctrl:1
	v_pk_fma_f32 v[4:5], v[116:117], v[120:121], v[112:113] op_sel_hi:[0,1,1]
	v_pk_fma_f32 v[6:7], v[116:117], v[122:123], v[114:115] op_sel_hi:[0,1,1]
	s_waitcnt lgkmcnt(13)
	v_pk_mul_f32 v[40:41], v[4:5], v[40:41]
	v_pk_fma_f32 v[40:41], v[6:7], v[42:43], v[40:41]
	v_add_f32_e32 v40, v40, v41
	v_pk_mul_f32 v[36:37], v[36:37], v[0:1] op_sel_hi:[1,0]
	v_pk_mul_f32 v[38:39], v[38:39], v[0:1] op_sel_hi:[1,0]
	v_add_f32_dpp v40, v40, v40 quad_perm:[1,0,3,2] row_mask:0xf bank_mask:0xf bound_ctrl:1
	v_pk_fma_f32 v[36:37], v[4:5], v[28:29], v[36:37]
	v_pk_fma_f32 v[38:39], v[6:7], v[30:31], v[38:39]
	v_add_f32_dpp v40, v40, v40 quad_perm:[2,3,0,1] row_mask:0xf bank_mask:0xf bound_ctrl:1
	v_pk_mul_f32 v[108:109], v[108:109], v[4:5]
	v_pk_fma_f32 v[108:109], v[6:7], v[110:111], v[108:109]
	v_add_f32_dpp v40, v40, v40 row_half_mirror row_mask:0xf bank_mask:0xf bound_ctrl:1
	v_add_f32_e32 v9, v108, v109
	ds_read_b128 v[112:115], v10 offset:17408
	ds_read_b128 v[116:119], v10 offset:17664
	ds_read_b128 v[104:107], v10 offset:16896
	ds_read_b128 v[120:123], v10 offset:17920
	ds_read_b128 v[108:111], v10 offset:17152
	v_add_f32_dpp v40, v40, v40 row_mirror row_mask:0xf bank_mask:0xf bound_ctrl:1
	v_pk_fma_f32 v[4:5], v[40:41], v[44:45], v[36:37] op_sel_hi:[0,1,1]
	v_pk_fma_f32 v[6:7], v[40:41], v[46:47], v[38:39] op_sel_hi:[0,1,1]
	s_waitcnt lgkmcnt(12)
	v_pk_mul_f32 v[60:61], v[4:5], v[60:61]
	v_pk_fma_f32 v[60:61], v[6:7], v[62:63], v[60:61]
	v_add_f32_e32 v60, v60, v61
	v_pk_mul_f32 v[56:57], v[56:57], v[0:1] op_sel:[0,1] op_sel_hi:[1,1]
	v_pk_mul_f32 v[58:59], v[58:59], v[0:1] op_sel:[0,1] op_sel_hi:[1,1]
	v_add_f32_dpp v60, v60, v60 quad_perm:[1,0,3,2] row_mask:0xf bank_mask:0xf bound_ctrl:1
	v_pk_fma_f32 v[56:57], v[4:5], v[48:49], v[56:57]
	v_pk_fma_f32 v[58:59], v[6:7], v[50:51], v[58:59]
	v_add_f32_dpp v60, v60, v60 quad_perm:[2,3,0,1] row_mask:0xf bank_mask:0xf bound_ctrl:1
	v_pk_mul_f32 v[32:33], v[32:33], v[4:5]
	v_pk_fma_f32 v[32:33], v[6:7], v[34:35], v[32:33]
	v_add_f32_dpp v60, v60, v60 row_half_mirror row_mask:0xf bank_mask:0xf bound_ctrl:1
	v_add_f32_e32 v8, v32, v33
	ds_read_b128 v[36:39], v10 offset:18944
	ds_read2st64_b32 v[0:1], v11 offset0:77 offset1:83
	ds_read_b128 v[40:43], v10 offset:19200
	ds_read_b128 v[28:31], v10 offset:18432
	ds_read_b128 v[44:47], v10 offset:19456
	ds_read_b128 v[32:35], v10 offset:18688
	ds_write2st64_b32 v12, v9, v8 offset0:20 offset1:22
	v_add_f32_dpp v60, v60, v60 row_mirror row_mask:0xf bank_mask:0xf bound_ctrl:1
	v_pk_fma_f32 v[4:5], v[60:61], v[64:65], v[56:57] op_sel_hi:[0,1,1]
	v_pk_fma_f32 v[6:7], v[60:61], v[66:67], v[58:59] op_sel_hi:[0,1,1]
	s_waitcnt lgkmcnt(13)
	v_pk_mul_f32 v[80:81], v[4:5], v[80:81]
	v_pk_fma_f32 v[80:81], v[6:7], v[82:83], v[80:81]
	v_add_f32_e32 v80, v80, v81
	v_pk_mul_f32 v[76:77], v[76:77], v[2:3] op_sel_hi:[1,0]
	v_pk_mul_f32 v[78:79], v[78:79], v[2:3] op_sel_hi:[1,0]
	v_add_f32_dpp v80, v80, v80 quad_perm:[1,0,3,2] row_mask:0xf bank_mask:0xf bound_ctrl:1
	v_pk_fma_f32 v[76:77], v[4:5], v[68:69], v[76:77]
	v_pk_fma_f32 v[78:79], v[6:7], v[70:71], v[78:79]
	v_add_f32_dpp v80, v80, v80 quad_perm:[2,3,0,1] row_mask:0xf bank_mask:0xf bound_ctrl:1
	v_pk_mul_f32 v[52:53], v[52:53], v[4:5]
	v_pk_fma_f32 v[52:53], v[6:7], v[54:55], v[52:53]
	v_add_f32_dpp v80, v80, v80 row_half_mirror row_mask:0xf bank_mask:0xf bound_ctrl:1
	v_add_f32_e32 v9, v52, v53
	ds_read_b128 v[56:59], v10 offset:20480
	ds_read_b128 v[60:63], v10 offset:20736
	ds_read_b128 v[48:51], v10 offset:19968
	ds_read_b128 v[64:67], v10 offset:20992
	ds_read_b128 v[52:55], v10 offset:20224
	v_add_f32_dpp v80, v80, v80 row_mirror row_mask:0xf bank_mask:0xf bound_ctrl:1
	v_pk_fma_f32 v[4:5], v[80:81], v[84:85], v[76:77] op_sel_hi:[0,1,1]
	v_pk_fma_f32 v[6:7], v[80:81], v[86:87], v[78:79] op_sel_hi:[0,1,1]
	s_waitcnt lgkmcnt(12)
	v_pk_mul_f32 v[116:117], v[4:5], v[116:117]
	v_pk_fma_f32 v[116:117], v[6:7], v[118:119], v[116:117]
	v_add_f32_e32 v116, v116, v117
	v_pk_mul_f32 v[112:113], v[112:113], v[2:3] op_sel:[0,1] op_sel_hi:[1,1]
	v_pk_mul_f32 v[114:115], v[114:115], v[2:3] op_sel:[0,1] op_sel_hi:[1,1]
	v_add_f32_dpp v116, v116, v116 quad_perm:[1,0,3,2] row_mask:0xf bank_mask:0xf bound_ctrl:1
	v_pk_fma_f32 v[112:113], v[4:5], v[104:105], v[112:113]
	v_pk_fma_f32 v[114:115], v[6:7], v[106:107], v[114:115]
	v_add_f32_dpp v116, v116, v116 quad_perm:[2,3,0,1] row_mask:0xf bank_mask:0xf bound_ctrl:1
	v_pk_mul_f32 v[72:73], v[72:73], v[4:5]
	v_pk_fma_f32 v[72:73], v[6:7], v[74:75], v[72:73]
	v_add_f32_dpp v116, v116, v116 row_half_mirror row_mask:0xf bank_mask:0xf bound_ctrl:1
	v_add_f32_e32 v8, v72, v73
	ds_read_b128 v[76:79], v10 offset:22016
	ds_read2st64_b32 v[2:3], v11 offset0:89 offset1:95
	ds_read_b128 v[80:83], v10 offset:22272
	ds_read_b128 v[68:71], v10 offset:21504
	ds_read_b128 v[84:87], v10 offset:22528
	ds_read_b128 v[72:75], v10 offset:21760
	ds_write2st64_b32 v12, v9, v8 offset0:24 offset1:26
	v_add_f32_dpp v116, v116, v116 row_mirror row_mask:0xf bank_mask:0xf bound_ctrl:1
	v_pk_fma_f32 v[4:5], v[116:117], v[120:121], v[112:113] op_sel_hi:[0,1,1]
	v_pk_fma_f32 v[6:7], v[116:117], v[122:123], v[114:115] op_sel_hi:[0,1,1]
	s_waitcnt lgkmcnt(13)
	v_pk_mul_f32 v[40:41], v[4:5], v[40:41]
	v_pk_fma_f32 v[40:41], v[6:7], v[42:43], v[40:41]
	v_add_f32_e32 v40, v40, v41
	v_pk_mul_f32 v[36:37], v[36:37], v[0:1] op_sel_hi:[1,0]
	v_pk_mul_f32 v[38:39], v[38:39], v[0:1] op_sel_hi:[1,0]
	v_add_f32_dpp v40, v40, v40 quad_perm:[1,0,3,2] row_mask:0xf bank_mask:0xf bound_ctrl:1
	v_pk_fma_f32 v[36:37], v[4:5], v[28:29], v[36:37]
	v_pk_fma_f32 v[38:39], v[6:7], v[30:31], v[38:39]
	v_add_f32_dpp v40, v40, v40 quad_perm:[2,3,0,1] row_mask:0xf bank_mask:0xf bound_ctrl:1
	v_pk_mul_f32 v[108:109], v[108:109], v[4:5]
	v_pk_fma_f32 v[108:109], v[6:7], v[110:111], v[108:109]
	v_add_f32_dpp v40, v40, v40 row_half_mirror row_mask:0xf bank_mask:0xf bound_ctrl:1
	v_add_f32_e32 v9, v108, v109
	ds_read_b128 v[112:115], v10 offset:23552
	ds_read_b128 v[116:119], v10 offset:23808
	ds_read_b128 v[104:107], v10 offset:23040
	ds_read_b128 v[120:123], v10 offset:24064
	ds_read_b128 v[108:111], v10 offset:23296
	v_add_f32_dpp v40, v40, v40 row_mirror row_mask:0xf bank_mask:0xf bound_ctrl:1
	v_pk_fma_f32 v[4:5], v[40:41], v[44:45], v[36:37] op_sel_hi:[0,1,1]
	v_pk_fma_f32 v[6:7], v[40:41], v[46:47], v[38:39] op_sel_hi:[0,1,1]
	s_waitcnt lgkmcnt(12)
	v_pk_mul_f32 v[60:61], v[4:5], v[60:61]
	v_pk_fma_f32 v[60:61], v[6:7], v[62:63], v[60:61]
	v_add_f32_e32 v60, v60, v61
	v_pk_mul_f32 v[56:57], v[56:57], v[0:1] op_sel:[0,1] op_sel_hi:[1,1]
	v_pk_mul_f32 v[58:59], v[58:59], v[0:1] op_sel:[0,1] op_sel_hi:[1,1]
	v_add_f32_dpp v60, v60, v60 quad_perm:[1,0,3,2] row_mask:0xf bank_mask:0xf bound_ctrl:1
	v_pk_fma_f32 v[56:57], v[4:5], v[48:49], v[56:57]
	v_pk_fma_f32 v[58:59], v[6:7], v[50:51], v[58:59]
	v_add_f32_dpp v60, v60, v60 quad_perm:[2,3,0,1] row_mask:0xf bank_mask:0xf bound_ctrl:1
	v_pk_mul_f32 v[32:33], v[32:33], v[4:5]
	v_pk_fma_f32 v[32:33], v[6:7], v[34:35], v[32:33]
	v_add_f32_dpp v60, v60, v60 row_half_mirror row_mask:0xf bank_mask:0xf bound_ctrl:1
	v_add_f32_e32 v8, v32, v33
	ds_read_b128 v[36:39], v10 offset:25088
	ds_read2st64_b32 v[0:1], v11 offset0:101 offset1:107
	ds_read_b128 v[40:43], v10 offset:25344
	ds_read_b128 v[28:31], v10 offset:24576
	ds_read_b128 v[44:47], v10 offset:25600
	ds_read_b128 v[32:35], v10 offset:24832
	ds_write2st64_b32 v12, v9, v8 offset0:28 offset1:30
	v_add_f32_dpp v60, v60, v60 row_mirror row_mask:0xf bank_mask:0xf bound_ctrl:1
	v_pk_fma_f32 v[4:5], v[60:61], v[64:65], v[56:57] op_sel_hi:[0,1,1]
	v_pk_fma_f32 v[6:7], v[60:61], v[66:67], v[58:59] op_sel_hi:[0,1,1]
	s_waitcnt lgkmcnt(13)
	v_pk_mul_f32 v[80:81], v[4:5], v[80:81]
	v_pk_fma_f32 v[80:81], v[6:7], v[82:83], v[80:81]
	v_add_f32_e32 v80, v80, v81
	v_pk_mul_f32 v[76:77], v[76:77], v[2:3] op_sel_hi:[1,0]
	v_pk_mul_f32 v[78:79], v[78:79], v[2:3] op_sel_hi:[1,0]
	v_add_f32_dpp v80, v80, v80 quad_perm:[1,0,3,2] row_mask:0xf bank_mask:0xf bound_ctrl:1
	v_pk_fma_f32 v[76:77], v[4:5], v[68:69], v[76:77]
	v_pk_fma_f32 v[78:79], v[6:7], v[70:71], v[78:79]
	v_add_f32_dpp v80, v80, v80 quad_perm:[2,3,0,1] row_mask:0xf bank_mask:0xf bound_ctrl:1
	v_pk_mul_f32 v[52:53], v[52:53], v[4:5]
	v_pk_fma_f32 v[52:53], v[6:7], v[54:55], v[52:53]
	v_add_f32_dpp v80, v80, v80 row_half_mirror row_mask:0xf bank_mask:0xf bound_ctrl:1
	v_add_f32_e32 v9, v52, v53
	ds_read_b128 v[56:59], v10 offset:26624
	ds_read_b128 v[60:63], v10 offset:26880
	ds_read_b128 v[48:51], v10 offset:26112
	ds_read_b128 v[64:67], v10 offset:27136
	ds_read_b128 v[52:55], v10 offset:26368
	v_add_f32_dpp v80, v80, v80 row_mirror row_mask:0xf bank_mask:0xf bound_ctrl:1
	v_pk_fma_f32 v[4:5], v[80:81], v[84:85], v[76:77] op_sel_hi:[0,1,1]
	v_pk_fma_f32 v[6:7], v[80:81], v[86:87], v[78:79] op_sel_hi:[0,1,1]
	s_waitcnt lgkmcnt(12)
	v_pk_mul_f32 v[116:117], v[4:5], v[116:117]
	v_pk_fma_f32 v[116:117], v[6:7], v[118:119], v[116:117]
	v_add_f32_e32 v116, v116, v117
	v_pk_mul_f32 v[112:113], v[112:113], v[2:3] op_sel:[0,1] op_sel_hi:[1,1]
	v_pk_mul_f32 v[114:115], v[114:115], v[2:3] op_sel:[0,1] op_sel_hi:[1,1]
	v_add_f32_dpp v116, v116, v116 quad_perm:[1,0,3,2] row_mask:0xf bank_mask:0xf bound_ctrl:1
	v_pk_fma_f32 v[112:113], v[4:5], v[104:105], v[112:113]
	v_pk_fma_f32 v[114:115], v[6:7], v[106:107], v[114:115]
	v_add_f32_dpp v116, v116, v116 quad_perm:[2,3,0,1] row_mask:0xf bank_mask:0xf bound_ctrl:1
	v_pk_mul_f32 v[72:73], v[72:73], v[4:5]
	v_pk_fma_f32 v[72:73], v[6:7], v[74:75], v[72:73]
	v_add_f32_dpp v116, v116, v116 row_half_mirror row_mask:0xf bank_mask:0xf bound_ctrl:1
	v_add_f32_e32 v8, v72, v73
	ds_read_b128 v[76:79], v10 offset:28160
	ds_read2st64_b32 v[2:3], v11 offset0:113 offset1:119
	ds_read_b128 v[80:83], v10 offset:28416
	ds_read_b128 v[68:71], v10 offset:27648
	ds_read_b128 v[84:87], v10 offset:28672
	ds_read_b128 v[72:75], v10 offset:27904
	ds_write2st64_b32 v12, v9, v8 offset0:32 offset1:34
	v_add_f32_dpp v116, v116, v116 row_mirror row_mask:0xf bank_mask:0xf bound_ctrl:1
	v_pk_fma_f32 v[4:5], v[116:117], v[120:121], v[112:113] op_sel_hi:[0,1,1]
	v_pk_fma_f32 v[6:7], v[116:117], v[122:123], v[114:115] op_sel_hi:[0,1,1]
	s_waitcnt lgkmcnt(13)
	v_pk_mul_f32 v[40:41], v[4:5], v[40:41]
	v_pk_fma_f32 v[40:41], v[6:7], v[42:43], v[40:41]
	v_add_f32_e32 v40, v40, v41
	v_pk_mul_f32 v[36:37], v[36:37], v[0:1] op_sel_hi:[1,0]
	v_pk_mul_f32 v[38:39], v[38:39], v[0:1] op_sel_hi:[1,0]
	v_add_f32_dpp v40, v40, v40 quad_perm:[1,0,3,2] row_mask:0xf bank_mask:0xf bound_ctrl:1
	v_pk_fma_f32 v[36:37], v[4:5], v[28:29], v[36:37]
	v_pk_fma_f32 v[38:39], v[6:7], v[30:31], v[38:39]
	v_add_f32_dpp v40, v40, v40 quad_perm:[2,3,0,1] row_mask:0xf bank_mask:0xf bound_ctrl:1
	v_pk_mul_f32 v[108:109], v[108:109], v[4:5]
	v_pk_fma_f32 v[108:109], v[6:7], v[110:111], v[108:109]
	v_add_f32_dpp v40, v40, v40 row_half_mirror row_mask:0xf bank_mask:0xf bound_ctrl:1
	v_add_f32_e32 v9, v108, v109
	ds_read_b128 v[112:115], v10 offset:29696
	ds_read_b128 v[116:119], v10 offset:29952
	ds_read_b128 v[104:107], v10 offset:29184
	ds_read_b128 v[120:123], v10 offset:30208
	ds_read_b128 v[108:111], v10 offset:29440
	v_add_f32_dpp v40, v40, v40 row_mirror row_mask:0xf bank_mask:0xf bound_ctrl:1
	v_pk_fma_f32 v[4:5], v[40:41], v[44:45], v[36:37] op_sel_hi:[0,1,1]
	v_pk_fma_f32 v[6:7], v[40:41], v[46:47], v[38:39] op_sel_hi:[0,1,1]
	s_waitcnt lgkmcnt(12)
	v_pk_mul_f32 v[60:61], v[4:5], v[60:61]
	v_pk_fma_f32 v[60:61], v[6:7], v[62:63], v[60:61]
	v_add_f32_e32 v60, v60, v61
	v_pk_mul_f32 v[56:57], v[56:57], v[0:1] op_sel:[0,1] op_sel_hi:[1,1]
	v_pk_mul_f32 v[58:59], v[58:59], v[0:1] op_sel:[0,1] op_sel_hi:[1,1]
	v_add_f32_dpp v60, v60, v60 quad_perm:[1,0,3,2] row_mask:0xf bank_mask:0xf bound_ctrl:1
	v_pk_fma_f32 v[56:57], v[4:5], v[48:49], v[56:57]
	v_pk_fma_f32 v[58:59], v[6:7], v[50:51], v[58:59]
	v_add_f32_dpp v60, v60, v60 quad_perm:[2,3,0,1] row_mask:0xf bank_mask:0xf bound_ctrl:1
	v_pk_mul_f32 v[32:33], v[32:33], v[4:5]
	v_pk_fma_f32 v[32:33], v[6:7], v[34:35], v[32:33]
	v_add_f32_dpp v60, v60, v60 row_half_mirror row_mask:0xf bank_mask:0xf bound_ctrl:1
	v_add_f32_e32 v8, v32, v33
	ds_read_b128 v[36:39], v10 offset:31232
	ds_read2st64_b32 v[0:1], v11 offset0:125 offset1:131
	ds_read_b128 v[40:43], v10 offset:31488
	ds_read_b128 v[28:31], v10 offset:30720
	ds_read_b128 v[44:47], v10 offset:31744
	ds_read_b128 v[32:35], v10 offset:30976
	ds_write2st64_b32 v12, v9, v8 offset0:36 offset1:38
	v_add_f32_dpp v60, v60, v60 row_mirror row_mask:0xf bank_mask:0xf bound_ctrl:1
	v_pk_fma_f32 v[4:5], v[60:61], v[64:65], v[56:57] op_sel_hi:[0,1,1]
	v_pk_fma_f32 v[6:7], v[60:61], v[66:67], v[58:59] op_sel_hi:[0,1,1]
	s_waitcnt lgkmcnt(13)
	v_pk_mul_f32 v[80:81], v[4:5], v[80:81]
	v_pk_fma_f32 v[80:81], v[6:7], v[82:83], v[80:81]
	v_add_f32_e32 v80, v80, v81
	v_pk_mul_f32 v[76:77], v[76:77], v[2:3] op_sel_hi:[1,0]
	v_pk_mul_f32 v[78:79], v[78:79], v[2:3] op_sel_hi:[1,0]
	v_add_f32_dpp v80, v80, v80 quad_perm:[1,0,3,2] row_mask:0xf bank_mask:0xf bound_ctrl:1
	v_pk_fma_f32 v[76:77], v[4:5], v[68:69], v[76:77]
	v_pk_fma_f32 v[78:79], v[6:7], v[70:71], v[78:79]
	v_add_f32_dpp v80, v80, v80 quad_perm:[2,3,0,1] row_mask:0xf bank_mask:0xf bound_ctrl:1
	v_pk_mul_f32 v[52:53], v[52:53], v[4:5]
	v_pk_fma_f32 v[52:53], v[6:7], v[54:55], v[52:53]
	v_add_f32_dpp v80, v80, v80 row_half_mirror row_mask:0xf bank_mask:0xf bound_ctrl:1
	v_add_f32_e32 v9, v52, v53
	ds_read_b128 v[56:59], v10 offset:32768
	ds_read_b128 v[60:63], v10 offset:33024
	ds_read_b128 v[48:51], v10 offset:32256
	ds_read_b128 v[64:67], v10 offset:33280
	ds_read_b128 v[52:55], v10 offset:32512
	v_add_f32_dpp v80, v80, v80 row_mirror row_mask:0xf bank_mask:0xf bound_ctrl:1
	v_pk_fma_f32 v[4:5], v[80:81], v[84:85], v[76:77] op_sel_hi:[0,1,1]
	v_pk_fma_f32 v[6:7], v[80:81], v[86:87], v[78:79] op_sel_hi:[0,1,1]
	s_waitcnt lgkmcnt(12)
	v_pk_mul_f32 v[116:117], v[4:5], v[116:117]
	v_pk_fma_f32 v[116:117], v[6:7], v[118:119], v[116:117]
	v_add_f32_e32 v116, v116, v117
	v_pk_mul_f32 v[112:113], v[112:113], v[2:3] op_sel:[0,1] op_sel_hi:[1,1]
	v_pk_mul_f32 v[114:115], v[114:115], v[2:3] op_sel:[0,1] op_sel_hi:[1,1]
	v_add_f32_dpp v116, v116, v116 quad_perm:[1,0,3,2] row_mask:0xf bank_mask:0xf bound_ctrl:1
	v_pk_fma_f32 v[112:113], v[4:5], v[104:105], v[112:113]
	v_pk_fma_f32 v[114:115], v[6:7], v[106:107], v[114:115]
	v_add_f32_dpp v116, v116, v116 quad_perm:[2,3,0,1] row_mask:0xf bank_mask:0xf bound_ctrl:1
	v_pk_mul_f32 v[72:73], v[72:73], v[4:5]
	v_pk_fma_f32 v[72:73], v[6:7], v[74:75], v[72:73]
	v_add_f32_dpp v116, v116, v116 row_half_mirror row_mask:0xf bank_mask:0xf bound_ctrl:1
	v_add_f32_e32 v8, v72, v73
	ds_read_b128 v[76:79], v10 offset:34304
	ds_read2st64_b32 v[2:3], v11 offset0:137 offset1:143
	ds_read_b128 v[80:83], v10 offset:34560
	ds_read_b128 v[68:71], v10 offset:33792
	ds_read_b128 v[84:87], v10 offset:34816
	ds_read_b128 v[72:75], v10 offset:34048
	ds_write2st64_b32 v12, v9, v8 offset0:40 offset1:42
	v_add_f32_dpp v116, v116, v116 row_mirror row_mask:0xf bank_mask:0xf bound_ctrl:1
	v_pk_fma_f32 v[4:5], v[116:117], v[120:121], v[112:113] op_sel_hi:[0,1,1]
	v_pk_fma_f32 v[6:7], v[116:117], v[122:123], v[114:115] op_sel_hi:[0,1,1]
	s_waitcnt lgkmcnt(13)
	v_pk_mul_f32 v[40:41], v[4:5], v[40:41]
	v_pk_fma_f32 v[40:41], v[6:7], v[42:43], v[40:41]
	v_add_f32_e32 v40, v40, v41
	v_pk_mul_f32 v[36:37], v[36:37], v[0:1] op_sel_hi:[1,0]
	v_pk_mul_f32 v[38:39], v[38:39], v[0:1] op_sel_hi:[1,0]
	v_add_f32_dpp v40, v40, v40 quad_perm:[1,0,3,2] row_mask:0xf bank_mask:0xf bound_ctrl:1
	v_pk_fma_f32 v[36:37], v[4:5], v[28:29], v[36:37]
	v_pk_fma_f32 v[38:39], v[6:7], v[30:31], v[38:39]
	v_add_f32_dpp v40, v40, v40 quad_perm:[2,3,0,1] row_mask:0xf bank_mask:0xf bound_ctrl:1
	v_pk_mul_f32 v[108:109], v[108:109], v[4:5]
	v_pk_fma_f32 v[108:109], v[6:7], v[110:111], v[108:109]
	v_add_f32_dpp v40, v40, v40 row_half_mirror row_mask:0xf bank_mask:0xf bound_ctrl:1
	v_add_f32_e32 v9, v108, v109
	ds_read_b128 v[112:115], v10 offset:35840
	ds_read_b128 v[116:119], v10 offset:36096
	ds_read_b128 v[104:107], v10 offset:35328
	ds_read_b128 v[120:123], v10 offset:36352
	ds_read_b128 v[108:111], v10 offset:35584
	v_add_f32_dpp v40, v40, v40 row_mirror row_mask:0xf bank_mask:0xf bound_ctrl:1
	v_pk_fma_f32 v[4:5], v[40:41], v[44:45], v[36:37] op_sel_hi:[0,1,1]
	v_pk_fma_f32 v[6:7], v[40:41], v[46:47], v[38:39] op_sel_hi:[0,1,1]
	s_waitcnt lgkmcnt(12)
	v_pk_mul_f32 v[60:61], v[4:5], v[60:61]
	v_pk_fma_f32 v[60:61], v[6:7], v[62:63], v[60:61]
	v_add_f32_e32 v60, v60, v61
	v_pk_mul_f32 v[56:57], v[56:57], v[0:1] op_sel:[0,1] op_sel_hi:[1,1]
	v_pk_mul_f32 v[58:59], v[58:59], v[0:1] op_sel:[0,1] op_sel_hi:[1,1]
	v_add_f32_dpp v60, v60, v60 quad_perm:[1,0,3,2] row_mask:0xf bank_mask:0xf bound_ctrl:1
	v_pk_fma_f32 v[56:57], v[4:5], v[48:49], v[56:57]
	v_pk_fma_f32 v[58:59], v[6:7], v[50:51], v[58:59]
	v_add_f32_dpp v60, v60, v60 quad_perm:[2,3,0,1] row_mask:0xf bank_mask:0xf bound_ctrl:1
	v_pk_mul_f32 v[32:33], v[32:33], v[4:5]
	v_pk_fma_f32 v[32:33], v[6:7], v[34:35], v[32:33]
	v_add_f32_dpp v60, v60, v60 row_half_mirror row_mask:0xf bank_mask:0xf bound_ctrl:1
	v_add_f32_e32 v8, v32, v33
	ds_read_b128 v[36:39], v10 offset:37376
	ds_read2st64_b32 v[0:1], v11 offset0:149 offset1:155
	ds_read_b128 v[40:43], v10 offset:37632
	ds_read_b128 v[28:31], v10 offset:36864
	ds_read_b128 v[44:47], v10 offset:37888
	ds_read_b128 v[32:35], v10 offset:37120
	ds_write2st64_b32 v12, v9, v8 offset0:44 offset1:46
	v_add_f32_dpp v60, v60, v60 row_mirror row_mask:0xf bank_mask:0xf bound_ctrl:1
	v_pk_fma_f32 v[4:5], v[60:61], v[64:65], v[56:57] op_sel_hi:[0,1,1]
	v_pk_fma_f32 v[6:7], v[60:61], v[66:67], v[58:59] op_sel_hi:[0,1,1]
	s_waitcnt lgkmcnt(13)
	v_pk_mul_f32 v[80:81], v[4:5], v[80:81]
	v_pk_fma_f32 v[80:81], v[6:7], v[82:83], v[80:81]
	v_add_f32_e32 v80, v80, v81
	v_pk_mul_f32 v[76:77], v[76:77], v[2:3] op_sel_hi:[1,0]
	v_pk_mul_f32 v[78:79], v[78:79], v[2:3] op_sel_hi:[1,0]
	v_add_f32_dpp v80, v80, v80 quad_perm:[1,0,3,2] row_mask:0xf bank_mask:0xf bound_ctrl:1
	v_pk_fma_f32 v[76:77], v[4:5], v[68:69], v[76:77]
	v_pk_fma_f32 v[78:79], v[6:7], v[70:71], v[78:79]
	v_add_f32_dpp v80, v80, v80 quad_perm:[2,3,0,1] row_mask:0xf bank_mask:0xf bound_ctrl:1
	v_pk_mul_f32 v[52:53], v[52:53], v[4:5]
	v_pk_fma_f32 v[52:53], v[6:7], v[54:55], v[52:53]
	v_add_f32_dpp v80, v80, v80 row_half_mirror row_mask:0xf bank_mask:0xf bound_ctrl:1
	v_add_f32_e32 v9, v52, v53
	ds_read_b128 v[56:59], v10 offset:38912
	ds_read_b128 v[60:63], v10 offset:39168
	ds_read_b128 v[48:51], v10 offset:38400
	ds_read_b128 v[64:67], v10 offset:39424
	ds_read_b128 v[52:55], v10 offset:38656
	v_add_f32_dpp v80, v80, v80 row_mirror row_mask:0xf bank_mask:0xf bound_ctrl:1
	v_pk_fma_f32 v[4:5], v[80:81], v[84:85], v[76:77] op_sel_hi:[0,1,1]
	v_pk_fma_f32 v[6:7], v[80:81], v[86:87], v[78:79] op_sel_hi:[0,1,1]
	s_waitcnt lgkmcnt(12)
	v_pk_mul_f32 v[116:117], v[4:5], v[116:117]
	v_pk_fma_f32 v[116:117], v[6:7], v[118:119], v[116:117]
	v_add_f32_e32 v116, v116, v117
	v_pk_mul_f32 v[112:113], v[112:113], v[2:3] op_sel:[0,1] op_sel_hi:[1,1]
	v_pk_mul_f32 v[114:115], v[114:115], v[2:3] op_sel:[0,1] op_sel_hi:[1,1]
	v_add_f32_dpp v116, v116, v116 quad_perm:[1,0,3,2] row_mask:0xf bank_mask:0xf bound_ctrl:1
	v_pk_fma_f32 v[112:113], v[4:5], v[104:105], v[112:113]
	v_pk_fma_f32 v[114:115], v[6:7], v[106:107], v[114:115]
	v_add_f32_dpp v116, v116, v116 quad_perm:[2,3,0,1] row_mask:0xf bank_mask:0xf bound_ctrl:1
	v_pk_mul_f32 v[72:73], v[72:73], v[4:5]
	v_pk_fma_f32 v[72:73], v[6:7], v[74:75], v[72:73]
	v_add_f32_dpp v116, v116, v116 row_half_mirror row_mask:0xf bank_mask:0xf bound_ctrl:1
	v_add_f32_e32 v8, v72, v73
	ds_read_b128 v[76:79], v10 offset:40448
	ds_read2st64_b32 v[2:3], v11 offset0:161 offset1:167
	ds_read_b128 v[80:83], v10 offset:40704
	ds_read_b128 v[68:71], v10 offset:39936
	ds_read_b128 v[84:87], v10 offset:40960
	ds_read_b128 v[72:75], v10 offset:40192
	ds_write2st64_b32 v12, v9, v8 offset0:48 offset1:50
	v_add_f32_dpp v116, v116, v116 row_mirror row_mask:0xf bank_mask:0xf bound_ctrl:1
	v_pk_fma_f32 v[4:5], v[116:117], v[120:121], v[112:113] op_sel_hi:[0,1,1]
	v_pk_fma_f32 v[6:7], v[116:117], v[122:123], v[114:115] op_sel_hi:[0,1,1]
	s_waitcnt lgkmcnt(13)
	v_pk_mul_f32 v[40:41], v[4:5], v[40:41]
	v_pk_fma_f32 v[40:41], v[6:7], v[42:43], v[40:41]
	v_add_f32_e32 v40, v40, v41
	v_pk_mul_f32 v[36:37], v[36:37], v[0:1] op_sel_hi:[1,0]
	v_pk_mul_f32 v[38:39], v[38:39], v[0:1] op_sel_hi:[1,0]
	v_add_f32_dpp v40, v40, v40 quad_perm:[1,0,3,2] row_mask:0xf bank_mask:0xf bound_ctrl:1
	v_pk_fma_f32 v[36:37], v[4:5], v[28:29], v[36:37]
	v_pk_fma_f32 v[38:39], v[6:7], v[30:31], v[38:39]
	v_add_f32_dpp v40, v40, v40 quad_perm:[2,3,0,1] row_mask:0xf bank_mask:0xf bound_ctrl:1
	v_pk_mul_f32 v[108:109], v[108:109], v[4:5]
	v_pk_fma_f32 v[108:109], v[6:7], v[110:111], v[108:109]
	v_add_f32_dpp v40, v40, v40 row_half_mirror row_mask:0xf bank_mask:0xf bound_ctrl:1
	v_add_f32_e32 v9, v108, v109
	ds_read_b128 v[112:115], v10 offset:41984
	ds_read_b128 v[116:119], v10 offset:42240
	ds_read_b128 v[104:107], v10 offset:41472
	ds_read_b128 v[120:123], v10 offset:42496
	ds_read_b128 v[108:111], v10 offset:41728
	v_add_f32_dpp v40, v40, v40 row_mirror row_mask:0xf bank_mask:0xf bound_ctrl:1
	v_pk_fma_f32 v[4:5], v[40:41], v[44:45], v[36:37] op_sel_hi:[0,1,1]
	v_pk_fma_f32 v[6:7], v[40:41], v[46:47], v[38:39] op_sel_hi:[0,1,1]
	s_waitcnt lgkmcnt(12)
	v_pk_mul_f32 v[60:61], v[4:5], v[60:61]
	v_pk_fma_f32 v[60:61], v[6:7], v[62:63], v[60:61]
	v_add_f32_e32 v60, v60, v61
	v_pk_mul_f32 v[56:57], v[56:57], v[0:1] op_sel:[0,1] op_sel_hi:[1,1]
	v_pk_mul_f32 v[58:59], v[58:59], v[0:1] op_sel:[0,1] op_sel_hi:[1,1]
	v_add_f32_dpp v60, v60, v60 quad_perm:[1,0,3,2] row_mask:0xf bank_mask:0xf bound_ctrl:1
	v_pk_fma_f32 v[56:57], v[4:5], v[48:49], v[56:57]
	v_pk_fma_f32 v[58:59], v[6:7], v[50:51], v[58:59]
	v_add_f32_dpp v60, v60, v60 quad_perm:[2,3,0,1] row_mask:0xf bank_mask:0xf bound_ctrl:1
	v_pk_mul_f32 v[32:33], v[32:33], v[4:5]
	v_pk_fma_f32 v[32:33], v[6:7], v[34:35], v[32:33]
	v_add_f32_dpp v60, v60, v60 row_half_mirror row_mask:0xf bank_mask:0xf bound_ctrl:1
	v_add_f32_e32 v8, v32, v33
	ds_read_b128 v[36:39], v10 offset:43520
	ds_read2st64_b32 v[0:1], v11 offset0:173 offset1:179
	ds_read_b128 v[40:43], v10 offset:43776
	ds_read_b128 v[28:31], v10 offset:43008
	ds_read_b128 v[44:47], v10 offset:44032
	ds_read_b128 v[32:35], v10 offset:43264
	ds_write2st64_b32 v12, v9, v8 offset0:52 offset1:54
	v_add_f32_dpp v60, v60, v60 row_mirror row_mask:0xf bank_mask:0xf bound_ctrl:1
	v_pk_fma_f32 v[4:5], v[60:61], v[64:65], v[56:57] op_sel_hi:[0,1,1]
	v_pk_fma_f32 v[6:7], v[60:61], v[66:67], v[58:59] op_sel_hi:[0,1,1]
	s_waitcnt lgkmcnt(13)
	v_pk_mul_f32 v[80:81], v[4:5], v[80:81]
	v_pk_fma_f32 v[80:81], v[6:7], v[82:83], v[80:81]
	v_add_f32_e32 v80, v80, v81
	v_pk_mul_f32 v[76:77], v[76:77], v[2:3] op_sel_hi:[1,0]
	v_pk_mul_f32 v[78:79], v[78:79], v[2:3] op_sel_hi:[1,0]
	v_add_f32_dpp v80, v80, v80 quad_perm:[1,0,3,2] row_mask:0xf bank_mask:0xf bound_ctrl:1
	v_pk_fma_f32 v[76:77], v[4:5], v[68:69], v[76:77]
	v_pk_fma_f32 v[78:79], v[6:7], v[70:71], v[78:79]
	v_add_f32_dpp v80, v80, v80 quad_perm:[2,3,0,1] row_mask:0xf bank_mask:0xf bound_ctrl:1
	v_pk_mul_f32 v[52:53], v[52:53], v[4:5]
	v_pk_fma_f32 v[52:53], v[6:7], v[54:55], v[52:53]
	v_add_f32_dpp v80, v80, v80 row_half_mirror row_mask:0xf bank_mask:0xf bound_ctrl:1
	v_add_f32_e32 v9, v52, v53
	ds_read_b128 v[56:59], v10 offset:45056
	ds_read_b128 v[60:63], v10 offset:45312
	ds_read_b128 v[48:51], v10 offset:44544
	ds_read_b128 v[64:67], v10 offset:45568
	ds_read_b128 v[52:55], v10 offset:44800
	v_add_f32_dpp v80, v80, v80 row_mirror row_mask:0xf bank_mask:0xf bound_ctrl:1
	v_pk_fma_f32 v[4:5], v[80:81], v[84:85], v[76:77] op_sel_hi:[0,1,1]
	v_pk_fma_f32 v[6:7], v[80:81], v[86:87], v[78:79] op_sel_hi:[0,1,1]
	s_waitcnt lgkmcnt(12)
	v_pk_mul_f32 v[116:117], v[4:5], v[116:117]
	v_pk_fma_f32 v[116:117], v[6:7], v[118:119], v[116:117]
	v_add_f32_e32 v116, v116, v117
	v_pk_mul_f32 v[112:113], v[112:113], v[2:3] op_sel:[0,1] op_sel_hi:[1,1]
	v_pk_mul_f32 v[114:115], v[114:115], v[2:3] op_sel:[0,1] op_sel_hi:[1,1]
	v_add_f32_dpp v116, v116, v116 quad_perm:[1,0,3,2] row_mask:0xf bank_mask:0xf bound_ctrl:1
	v_pk_fma_f32 v[112:113], v[4:5], v[104:105], v[112:113]
	v_pk_fma_f32 v[114:115], v[6:7], v[106:107], v[114:115]
	v_add_f32_dpp v116, v116, v116 quad_perm:[2,3,0,1] row_mask:0xf bank_mask:0xf bound_ctrl:1
	v_pk_mul_f32 v[72:73], v[72:73], v[4:5]
	v_pk_fma_f32 v[72:73], v[6:7], v[74:75], v[72:73]
	v_add_f32_dpp v116, v116, v116 row_half_mirror row_mask:0xf bank_mask:0xf bound_ctrl:1
	v_add_f32_e32 v8, v72, v73
	ds_read_b128 v[76:79], v10 offset:46592
	ds_read2st64_b32 v[2:3], v11 offset0:185 offset1:191
	ds_read_b128 v[80:83], v10 offset:46848
	ds_read_b128 v[68:71], v10 offset:46080
	ds_read_b128 v[84:87], v10 offset:47104
	ds_read_b128 v[72:75], v10 offset:46336
	ds_write2st64_b32 v12, v9, v8 offset0:56 offset1:58
	v_add_f32_dpp v116, v116, v116 row_mirror row_mask:0xf bank_mask:0xf bound_ctrl:1
	v_pk_fma_f32 v[4:5], v[116:117], v[120:121], v[112:113] op_sel_hi:[0,1,1]
	v_pk_fma_f32 v[6:7], v[116:117], v[122:123], v[114:115] op_sel_hi:[0,1,1]
	s_waitcnt lgkmcnt(13)
	v_pk_mul_f32 v[40:41], v[4:5], v[40:41]
	v_pk_fma_f32 v[40:41], v[6:7], v[42:43], v[40:41]
	v_add_f32_e32 v40, v40, v41
	v_pk_mul_f32 v[36:37], v[36:37], v[0:1] op_sel_hi:[1,0]
	v_pk_mul_f32 v[38:39], v[38:39], v[0:1] op_sel_hi:[1,0]
	v_add_f32_dpp v40, v40, v40 quad_perm:[1,0,3,2] row_mask:0xf bank_mask:0xf bound_ctrl:1
	v_pk_fma_f32 v[36:37], v[4:5], v[28:29], v[36:37]
	v_pk_fma_f32 v[38:39], v[6:7], v[30:31], v[38:39]
	v_add_f32_dpp v40, v40, v40 quad_perm:[2,3,0,1] row_mask:0xf bank_mask:0xf bound_ctrl:1
	v_pk_mul_f32 v[108:109], v[108:109], v[4:5]
	v_pk_fma_f32 v[108:109], v[6:7], v[110:111], v[108:109]
	v_add_f32_dpp v40, v40, v40 row_half_mirror row_mask:0xf bank_mask:0xf bound_ctrl:1
	v_add_f32_e32 v9, v108, v109
	ds_read_b128 v[112:115], v10 offset:48128
	ds_read_b128 v[116:119], v10 offset:48384
	ds_read_b128 v[104:107], v10 offset:47616
	ds_read_b128 v[120:123], v10 offset:48640
	ds_read_b128 v[108:111], v10 offset:47872
	v_add_f32_dpp v40, v40, v40 row_mirror row_mask:0xf bank_mask:0xf bound_ctrl:1
	v_pk_fma_f32 v[4:5], v[40:41], v[44:45], v[36:37] op_sel_hi:[0,1,1]
	v_pk_fma_f32 v[6:7], v[40:41], v[46:47], v[38:39] op_sel_hi:[0,1,1]
	s_waitcnt lgkmcnt(12)
	v_pk_mul_f32 v[60:61], v[4:5], v[60:61]
	v_pk_fma_f32 v[60:61], v[6:7], v[62:63], v[60:61]
	v_add_f32_e32 v60, v60, v61
	v_pk_mul_f32 v[56:57], v[56:57], v[0:1] op_sel:[0,1] op_sel_hi:[1,1]
	v_pk_mul_f32 v[58:59], v[58:59], v[0:1] op_sel:[0,1] op_sel_hi:[1,1]
	v_add_f32_dpp v60, v60, v60 quad_perm:[1,0,3,2] row_mask:0xf bank_mask:0xf bound_ctrl:1
	v_pk_fma_f32 v[56:57], v[4:5], v[48:49], v[56:57]
	v_pk_fma_f32 v[58:59], v[6:7], v[50:51], v[58:59]
	v_add_f32_dpp v60, v60, v60 quad_perm:[2,3,0,1] row_mask:0xf bank_mask:0xf bound_ctrl:1
	v_pk_mul_f32 v[32:33], v[32:33], v[4:5]
	v_pk_fma_f32 v[32:33], v[6:7], v[34:35], v[32:33]
	v_add_f32_dpp v60, v60, v60 row_half_mirror row_mask:0xf bank_mask:0xf bound_ctrl:1
	v_add_f32_e32 v8, v32, v33
	ds_write2st64_b32 v12, v9, v8 offset0:60 offset1:62
	s_nop 0
	v_add_f32_dpp v60, v60, v60 row_mirror row_mask:0xf bank_mask:0xf bound_ctrl:1

.LBB0_826:
	s_and_saveexec_b64 s[8:9], s[26:27]
	s_cbranch_execz .Lscan_epi_done
	v_mov_b32_e32 v12, v102
	v_pk_fma_f32 v[4:5], v[60:61], v[64:65], v[56:57] op_sel_hi:[0,1,1]
	v_pk_fma_f32 v[6:7], v[60:61], v[66:67], v[58:59] op_sel_hi:[0,1,1]
	v_pk_mul_f32 v[80:81], v[4:5], v[80:81]
	v_pk_fma_f32 v[80:81], v[6:7], v[82:83], v[80:81]
	v_add_f32_e32 v80, v80, v81
	v_pk_mul_f32 v[76:77], v[76:77], v[2:3] op_sel_hi:[1,0]
	v_pk_mul_f32 v[78:79], v[78:79], v[2:3] op_sel_hi:[1,0]
	v_add_f32_dpp v80, v80, v80 quad_perm:[1,0,3,2] row_mask:0xf bank_mask:0xf bound_ctrl:1
	v_pk_fma_f32 v[76:77], v[4:5], v[68:69], v[76:77]
	v_pk_fma_f32 v[78:79], v[6:7], v[70:71], v[78:79]
	v_add_f32_dpp v80, v80, v80 quad_perm:[2,3,0,1] row_mask:0xf bank_mask:0xf bound_ctrl:1
	v_pk_mul_f32 v[52:53], v[52:53], v[4:5]
	v_pk_fma_f32 v[52:53], v[6:7], v[54:55], v[52:53]
	v_add_f32_dpp v80, v80, v80 row_half_mirror row_mask:0xf bank_mask:0xf bound_ctrl:1
	v_add_f32_e32 v9, v52, v53
	s_nop 0
	v_add_f32_dpp v80, v80, v80 row_mirror row_mask:0xf bank_mask:0xf bound_ctrl:1
	v_pk_fma_f32 v[4:5], v[80:81], v[84:85], v[76:77] op_sel_hi:[0,1,1]
	v_pk_fma_f32 v[6:7], v[80:81], v[86:87], v[78:79] op_sel_hi:[0,1,1]
	v_pk_mul_f32 v[116:117], v[4:5], v[116:117]
	v_pk_fma_f32 v[116:117], v[6:7], v[118:119], v[116:117]
	v_add_f32_e32 v116, v116, v117
	v_pk_mul_f32 v[112:113], v[112:113], v[2:3] op_sel:[0,1] op_sel_hi:[1,1]
	v_pk_mul_f32 v[114:115], v[114:115], v[2:3] op_sel:[0,1] op_sel_hi:[1,1]
	v_add_f32_dpp v116, v116, v116 quad_perm:[1,0,3,2] row_mask:0xf bank_mask:0xf bound_ctrl:1
	v_pk_fma_f32 v[112:113], v[4:5], v[104:105], v[112:113]
	v_pk_fma_f32 v[114:115], v[6:7], v[106:107], v[114:115]
	v_add_f32_dpp v116, v116, v116 quad_perm:[2,3,0,1] row_mask:0xf bank_mask:0xf bound_ctrl:1
	v_pk_mul_f32 v[72:73], v[72:73], v[4:5]
	v_pk_fma_f32 v[72:73], v[6:7], v[74:75], v[72:73]
	v_add_f32_dpp v116, v116, v116 row_half_mirror row_mask:0xf bank_mask:0xf bound_ctrl:1
	v_add_f32_e32 v8, v72, v73
	ds_write2st64_b32 v12, v9, v8 offset0:0 offset1:2
	s_nop 0
	v_add_f32_dpp v116, v116, v116 row_mirror row_mask:0xf bank_mask:0xf bound_ctrl:1
	v_pk_fma_f32 v[4:5], v[116:117], v[120:121], v[112:113] op_sel_hi:[0,1,1]
	v_pk_fma_f32 v[6:7], v[116:117], v[122:123], v[114:115] op_sel_hi:[0,1,1]
	v_pk_mul_f32 v[108:109], v[108:109], v[4:5]
	v_pk_fma_f32 v[108:109], v[6:7], v[110:111], v[108:109]
	v_add_f32_e32 v9, v108, v109
	ds_write_b32 v12, v9 offset:1024
	s_nop 0
